# row-pass norm-gain loads issued together behind one wait (fast path when both gain vectors present)
# speedup vs baseline: 1.0034x; 1.0034x over previous
; __device__ __forceinline__ void row_pass(const RowArgs& R, int gw, int NGW, int lane, LAS unsigned char* lds, int tid) {
;     float gp[2][8], gn[2][8];
; #pragma unroll
;     for (int j = 0; j < 2; ++j)
; #pragma unroll
;         for (int h = 0; h < 2; ++h) {
;             const f32x4 a = R.gpost ? *(const f32x4*)(R.gpost + 8 * lane + 512 * j + 4 * h) : (f32x4){0.f, 0.f, 0.f, 0.f};
;             const f32x4 b = R.gnext ? *(const f32x4*)(R.gnext + 8 * lane + 512 * j + 4 * h) : (f32x4){0.f, 0.f, 0.f, 0.f};
; #pragma unroll
;             for (int e = 0; e < 4; ++e) { gp[j][4 * h + e] = a[e]; gn[j][4 * h + e] = b[e]; }
;         }
;     const f32x4 bf = R.AF ? *(const f32x4*)R.bforget : (f32x4){0.f, 0.f, 0.f, 0.f};
.LBB0_216:
	s_cmp_eq_u64 s[8:9], 0
	s_cbranch_scc1 .Lrp_slowgain
	s_cmp_eq_u64 s[6:7], 0
	s_cbranch_scc1 .Lrp_slowgain
	v_and_b32_e32 v80, 63, v36
	v_lshlrev_b32_e32 v0, 5, v80
	s_mov_b64 s[34:35], -1
	v_lshl_add_u64 v[26:27], s[8:9], 0, v[0:1]
	v_lshlrev_b32_e32 v142, 3, v80
	v_lshlrev_b32_e32 v0, 2, v142
	s_mov_b64 s[36:37], -1
	v_lshl_add_u64 v[32:33], s[6:7], 0, v[0:1]
	global_load_dwordx4 v[6:9], v[26:27], off
	global_load_dwordx4 v[2:5], v[32:33], off
	global_load_dwordx4 v[12:15], v[26:27], off offset:16
	global_load_dwordx4 v[84:87], v[32:33], off offset:16
	global_load_dwordx4 v[20:23], v[26:27], off offset:2048
	global_load_dwordx4 v[16:19], v[32:33], off offset:2048
	global_load_dwordx4 v[28:31], v[26:27], off offset:2064
	global_load_dwordx4 v[88:91], v[32:33], off offset:2064
	s_mov_b64 s[8:9], 0
	s_mov_b64 s[6:7], 0
	s_mov_b64 vcc, 0
	s_waitcnt vmcnt(0)
	v_mov_b32_e32 v196, v7
	v_mov_b32_e32 v7, v8
	v_mov_b32_e32 v140, v9
	v_mov_b32_e32 v144, v3
	v_mov_b32_e32 v3, v4
	v_mov_b32_e32 v145, v5
	v_mov_b32_e32 v141, v13
	v_mov_b32_e32 v13, v14
	v_mov_b32_e32 v8, v84
	v_mov_b32_e32 v4, v85
	v_mov_b32_e32 v9, v86
	v_mov_b32_e32 v5, v87
	v_mov_b32_e32 v10, v17
	v_mov_b32_e32 v17, v18
	v_mov_b32_e32 v11, v19
	v_mov_b32_e32 v14, v30
	v_mov_b32_e32 v24, v88
	v_mov_b32_e32 v18, v89
	v_mov_b32_e32 v25, v90
	v_mov_b32_e32 v19, v91
	v_mov_b32_e32 v0, 1
	s_branch .LBB0_232
	s_nop 0
	s_nop 0
	s_nop 0
	s_nop 0
	s_nop 0
	s_nop 0
	s_nop 0
	s_nop 0
